# P7 tail: deferred w_ff2 conversion on 4 of the 8 waves of the non-GEMM workgroups (half the outstanding conversion loads) so the sample rows' GEMM, which shares HBM with it, finishes sooner
# speedup vs baseline: 1.0004x; 1.0004x over previous
.LBB0_844:
	v_readlane_b32 s0, v255, 16
	v_readlane_b32 s1, v255, 17
	s_andn2_b64 vcc, exec, s[0:1]
	s_cbranch_vccnz .LBB0_864
	s_sub_i32 s0, s2, s35
	s_lshl_b32 s0, s0, 2
	v_readlane_b32 s1, v255, 5
	s_add_i32 s0, s0, s1
	s_cmp_gt_u32 s1, 3
	s_cbranch_scc1 .LBB0_864
	s_cmpk_gt_u32 s0, 0xfff
	s_cbranch_scc1 .LBB0_864
	s_waitcnt vmcnt(15)
	v_and_b32_e32 v2, 28, v171
	v_readlane_b32 s1, v255, 5
	s_waitcnt vmcnt(10)
	v_lshlrev_b32_e32 v22, 2, v2
	v_lshlrev_b32_e32 v2, 3, v0
	s_lshl_b32 s1, s1, 14
	v_lshrrev_b32_e32 v24, 3, v170
	v_and_b32_e32 v2, 56, v2
	s_add_i32 s1, s1, 0
	v_mul_u32_u24_e32 v6, 0x84, v2
	v_lshlrev_b32_e32 v7, 2, v24
	s_waitcnt vmcnt(9)
	v_add_u32_e32 v29, s1, v22
	v_readlane_b32 s8, v255, 6
	v_add3_u32 v28, s1, v6, v7
	s_sub_i32 s3, s2, s35
	s_waitcnt vmcnt(8)
	v_mul_u32_u24_e32 v30, 0x84, v24
	v_lshlrev_b32_e32 v2, 1, v2
	v_mov_b32_e32 v3, 0
	v_readlane_b32 s9, v255, 7
	s_lshr_b32 s1, s1, 14
	s_lshl2_add_u32 s3, s3, s1
	s_sub_i32 s0, s96, s35
	v_lshl_add_u64 v[4:5], s[8:9], 0, v[2:3]
	v_mov_b32_e32 v23, v3
	s_add_i32 s1, s3, 0x2c00
	s_lshl_b32 s3, s3, 5
	s_lshl_b32 s6, s96, 7
	s_lshl_b32 s8, s35, 7
	v_add_u32_e32 v29, v29, v30
	s_lshl_b32 s0, s0, 2
	s_mov_b32 s7, 0
	v_or_b32_e32 v25, 8, v24
	v_or_b32_e32 v26, 16, v24
	v_or_b32_e32 v27, 24, v24
	v_lshl_add_u64 v[6:7], s[78:79], 0, v[2:3]
	v_lshl_add_u64 v[8:9], s[82:83], 0, v[2:3]
	v_lshl_add_u64 v[10:11], s[80:81], 0, v[2:3]
	v_lshl_add_u64 v[12:13], s[76:77], 0, v[2:3]
	v_lshl_add_u64 v[14:15], s[22:23], 0, v[22:23]
	v_lshl_add_u64 v[16:17], s[18:19], 0, v[22:23]
	v_lshl_add_u64 v[18:19], s[46:47], 0, v[22:23]
	v_lshl_add_u64 v[20:21], s[48:49], 0, v[22:23]
	v_lshl_add_u64 v[22:23], s[36:37], 0, v[22:23]
	s_add_i32 s3, s3, 0x98000
	s_sub_i32 s10, s6, s8
	v_add_u32_e32 v30, 0x420, v29
	v_add_u32_e32 v31, 0x428, v29
	v_add_u32_e32 v32, 0x840, v29
	v_add_u32_e32 v33, 0x848, v29
	s_waitcnt vmcnt(7)
	v_add_u32_e32 v34, 0xc60, v29
	v_add_u32_e32 v35, 0xc68, v29
	v_add_u32_e32 v36, 0x1080, v29
	v_add_u32_e32 v37, 0x1088, v29
	s_waitcnt vmcnt(6)
	v_add_u32_e32 v38, 0x14a0, v29
	v_add_u32_e32 v39, 0x14a8, v29
	v_add_u32_e32 v40, 0x18c0, v29
	v_add_u32_e32 v41, 0x18c8, v29
	s_waitcnt vmcnt(5)
	v_add_u32_e32 v42, 0x1ce0, v29
	v_add_u32_e32 v43, 0x1ce8, v29
	s_movk_i32 s11, 0x7fff
	s_mov_b32 s16, 0xffff0000
	s_mov_b32 s17, 0x40000
	s_branch .LBB0_848
